# rotated leftover prep/pool items away from natten-heavy workgroups; natten next-block K loads issued ahead of bias select
# speedup vs baseline: 1.1108x; 1.0061x over previous
; template <bool CL>
; __device__ __forceinline__ void natten_wave(const Params& p, int l, bool local, int b, int hh, int qrow0  ,
;                             int r, int ct, const f16* lK, const f16* lV) {
;     ...
; #pragma unroll
;     for (int kr = 0; kr < 8; ++kr) {
; #pragma unroll
;       for (int blk = 0; blk < 2; ++blk) {
;         int tk = (rs + kr) * GW + col0 + kperm + 4 * blk;
;         const f16* kp = proj + (size_t)(b * TL + tk) * PJ + RD + hh * HD + g * 16;
;         f16x8 k0 = *(const f16x8*)(kp);
;         f16x8 k1 = *(const f16x8*)(kp + 8);
;         f32x4 a = f32x4{0.f, 0.f, 0.f, 0.f};
;         a = __builtin_amdgcn_mfma_f32_16x16x32_f16(k0, qf[0], a, 0, 0, 0);
;         a = __builtin_amdgcn_mfma_f32_16x16x32_f16(k1, qf[1], a, 0, 0, 0);
;         const float* bp = rpb + (rs + kr - r + 7) * 31;
; #pragma unroll
;         for (int i = 0; i < 4; ++i) {
;           int kc = col0 + 8 * g + 4 * blk + i;
;           bool valid = (kc >= cs) && (kc <= cs + 15);
;           int bi = kc - c + 15;
;           bi = bi < 0 ? 0 : (bi > 30 ? 30 : bi);
;           float s = valid ? a[i] + bp[bi] : -1e30f;
;           a[i] = s;
;           mx = fmaxf(mx, s);
;         }
;         sl[kr][blk] = a;
;       }
;     }
.LBB0_557:
	v_med3_i32 v10, s38, 4, v188
	v_lshlrev_b32_e32 v4, 6, v10
	v_add_u32_e32 v11, s12, v114
	v_add_u32_e32 v68, 0xffffff00, v4
	v_add_u32_e32 v18, v11, v68
	v_mul_hi_i32_i24_e32 v5, 0x1440, v18
	v_mul_i32_i24_e32 v4, 0x1440, v18
	v_lshl_add_u64 v[8:9], v[90:91], 0, v[4:5]
	global_load_dwordx4 v[4:7], v[8:9], off offset:768
	global_load_dwordx4 v[12:15], v[8:9], off offset:784
	v_add_u32_e32 v8, s40, v10
	v_readfirstlane_b32 s41, v10
	v_mul_lo_u32 v10, v8, 31
	v_add_u32_e32 v8, 0xffffff27, v10
	v_ashrrev_i32_e32 v9, 31, v8
	v_add_u32_e32 v107, s12, v115
	v_lshlrev_b64 v[8:9], 2, v[8:9]
	v_cmp_ge_u32_e32 vcc, v107, v113
	v_cmp_le_u32_e64 s[6:7], v107, v116
	v_lshl_add_u64 v[26:27], v[92:93], 0, v[8:9]
	v_sub_u32_e32 v8, v107, v111
	s_and_b64 s[10:11], vcc, s[6:7]
	v_mov_b32_e32 v69, 0xf149f2ca
	v_med3_i32 v8, v8, -15, 15
	v_mov_b32_e32 v70, 0xf149f2ca
	s_waitcnt vmcnt(1)
	v_mfma_f32_16x16x32_f16 v[4:7], v[4:7], v[64:67], 0
	s_waitcnt vmcnt(0)
	v_mfma_f32_16x16x32_f16 v[4:7], v[12:15], v[0:3], v[4:7]
	s_nop 7
	v_mov_b32_e32 v244, v4
	v_mov_b32_e32 v245, v5
	v_mov_b32_e32 v246, v6
	v_mov_b32_e32 v247, v7
	v_ashrrev_i32_e32 v9, 31, v8
	v_lshl_add_u64 v[12:13], v[8:9], 2, v[26:27]
	global_load_dword v248, v[12:13], off offset:928
	s_nop 4
	v_or_b32_e32 v4, 1, v107
	v_cmp_ge_u32_e32 vcc, v4, v113
	v_cmp_lt_u32_e64 s[6:7], v107, v116
	v_sub_u32_e32 v4, v4, v111
	s_and_b64 s[12:13], vcc, s[6:7]
	v_med3_i32 v12, v4, -15, 15
	v_ashrrev_i32_e32 v13, 31, v12
	v_lshl_add_u64 v[14:15], v[12:13], 2, v[26:27]
	global_load_dword v249, v[14:15], off offset:928
	v_or_b32_e32 v4, 2, v107
	v_cmp_ge_u32_e32 vcc, v4, v113
	v_cmp_le_u32_e64 s[6:7], v4, v116
	v_sub_u32_e32 v4, v4, v111
	s_and_b64 s[14:15], vcc, s[6:7]
	v_mov_b32_e32 v71, 0xf149f2ca
	v_med3_i32 v14, v4, -15, 15
	v_mov_b32_e32 v72, 0xf149f2ca
	v_ashrrev_i32_e32 v15, 31, v14
	v_lshl_add_u64 v[4:5], v[14:15], 2, v[26:27]
	global_load_dword v250, v[4:5], off offset:928
	v_or_b32_e32 v4, 3, v107
	v_cmp_ge_u32_e32 vcc, v4, v113
	v_cmp_le_u32_e64 s[6:7], v4, v116
	v_sub_u32_e32 v4, v4, v111
	s_and_b64 s[16:17], vcc, s[6:7]
	v_med3_i32 v16, v4, -15, 15
	v_ashrrev_i32_e32 v17, 31, v16
	v_lshl_add_u64 v[4:5], v[16:17], 2, v[26:27]
	global_load_dword v251, v[4:5], off offset:928
	v_or_b32_e32 v4, 4, v18
	v_mad_i64_i32 v[18:19], s[6:7], v4, s22, v[90:91]
	global_load_dwordx4 v[4:7], v[18:19], off offset:768
	s_nop 0
	global_load_dwordx4 v[18:21], v[18:19], off offset:784
	v_or_b32_e32 v9, 4, v107
	v_cmp_ge_u32_e32 vcc, v9, v113
	v_cmp_le_u32_e64 s[6:7], v9, v116
	v_sub_u32_e32 v9, v9, v111
	s_and_b64 s[18:19], vcc, s[6:7]
	v_mov_b32_e32 v73, 0xf149f2ca
	v_mov_b32_e32 v74, 0xf149f2ca
	s_waitcnt vmcnt(2)
	v_add_f32_e32 v248, v244, v248
	v_cndmask_b32_e64 v70, v70, v248, s[10:11]
	v_add_f32_e32 v249, v245, v249
	v_cndmask_b32_e64 v69, v69, v249, s[12:13]
	v_add_f32_e32 v250, v246, v250
	v_cndmask_b32_e64 v72, v72, v250, s[14:15]
	v_add_f32_e32 v251, v247, v251
	v_cndmask_b32_e64 v71, v71, v251, s[16:17]
	s_waitcnt vmcnt(1)
	v_mfma_f32_16x16x32_f16 v[4:7], v[4:7], v[64:67], 0
	s_waitcnt vmcnt(0)
	v_mfma_f32_16x16x32_f16 v[4:7], v[18:21], v[0:3], v[4:7]
	v_med3_i32 v18, v9, -15, 15
	s_nop 7
	v_mov_b32_e32 v244, v4
	v_mov_b32_e32 v245, v5
	v_mov_b32_e32 v246, v6
	v_mov_b32_e32 v247, v7
	v_ashrrev_i32_e32 v19, 31, v18
	v_lshl_add_u64 v[20:21], v[18:19], 2, v[26:27]
	global_load_dword v248, v[20:21], off offset:928
	s_nop 3
	v_or_b32_e32 v4, 5, v107
	v_cmp_ge_u32_e32 vcc, v4, v113
	v_cmp_le_u32_e64 s[6:7], v4, v116
	v_sub_u32_e32 v4, v4, v111
	s_and_b64 s[20:21], vcc, s[6:7]
	v_med3_i32 v20, v4, -15, 15
	v_ashrrev_i32_e32 v21, 31, v20
	v_lshl_add_u64 v[22:23], v[20:21], 2, v[26:27]
	global_load_dword v249, v[22:23], off offset:928
	v_or_b32_e32 v4, 6, v107
	v_cmp_ge_u32_e32 vcc, v4, v113
	v_cmp_le_u32_e64 s[6:7], v4, v116
	v_sub_u32_e32 v4, v4, v111
	s_and_b64 s[34:35], vcc, s[6:7]
	v_mov_b32_e32 v75, 0xf149f2ca
	v_med3_i32 v22, v4, -15, 15
	v_mov_b32_e32 v76, 0xf149f2ca
	v_ashrrev_i32_e32 v23, 31, v22
	v_lshl_add_u64 v[4:5], v[22:23], 2, v[26:27]
	global_load_dword v250, v[4:5], off offset:928
	v_or_b32_e32 v4, 7, v107
	v_cmp_ge_u32_e32 vcc, v4, v113
	v_cmp_le_u32_e64 s[6:7], v107, v112
	v_sub_u32_e32 v4, v4, v111
	s_and_b64 s[6:7], vcc, s[6:7]
	v_med3_i32 v24, v4, -15, 15
	v_ashrrev_i32_e32 v25, 31, v24
	v_lshl_add_u64 v[4:5], v[24:25], 2, v[26:27]
	global_load_dword v251, v[4:5], off offset:928
	s_lshl_b32 s41, s41, 6
	s_add_i32 s48, s41, 0xffffff40
	v_add_u32_e32 v19, s48, v11
	v_mul_hi_i32_i24_e32 v5, 0x1440, v19
	v_mul_i32_i24_e32 v4, 0x1440, v19
	v_lshl_add_u64 v[26:27], v[90:91], 0, v[4:5]
	global_load_dwordx4 v[4:7], v[26:27], off offset:768
	global_load_dwordx4 v[28:31], v[26:27], off offset:784
	v_add_u32_e32 v26, 0xffffff46, v10
	v_ashrrev_i32_e32 v27, 31, v26
	v_lshlrev_b64 v[26:27], 2, v[26:27]
	v_lshl_add_u64 v[26:27], v[92:93], 0, v[26:27]
	v_mov_b32_e32 v160, 0xf149f2ca
	v_mov_b32_e32 v161, 0xf149f2ca
	s_waitcnt vmcnt(2)
	v_add_f32_e32 v248, v244, v248
	v_cndmask_b32_e64 v74, v74, v248, s[18:19]
	v_add_f32_e32 v249, v245, v249
	v_cndmask_b32_e64 v73, v73, v249, s[20:21]
	v_add_f32_e32 v250, v246, v250
	v_cndmask_b32_e64 v76, v76, v250, s[34:35]
	v_add_f32_e32 v251, v247, v251
	v_cndmask_b32_e64 v75, v75, v251, s[6:7]
	s_waitcnt vmcnt(1)
	v_mfma_f32_16x16x32_f16 v[4:7], v[4:7], v[64:67], 0
	s_waitcnt vmcnt(0)
; template <bool CL>
; __device__ __forceinline__ void natten_wave(const Params& p, int l, bool local, int b, int hh, int qrow0  ,
;                             int r, int ct, const f16* lK, const f16* lV) {
;     ...
; #pragma unroll
;     for (int kr = 0; kr < 8; ++kr) {
; #pragma unroll
;       for (int blk = 0; blk < 2; ++blk) {
;         int tk = (rs + kr) * GW + col0 + kperm + 4 * blk;
;         const f16* kp = proj + (size_t)(b * TL + tk) * PJ + RD + hh * HD + g * 16;
;         f16x8 k0 = *(const f16x8*)(kp);
;         f16x8 k1 = *(const f16x8*)(kp + 8);
;         f32x4 a = f32x4{0.f, 0.f, 0.f, 0.f};
;         a = __builtin_amdgcn_mfma_f32_16x16x32_f16(k0, qf[0], a, 0, 0, 0);
;         a = __builtin_amdgcn_mfma_f32_16x16x32_f16(k1, qf[1], a, 0, 0, 0);
;         const float* bp = rpb + (rs + kr - r + 7) * 31;
; #pragma unroll
;         for (int i = 0; i < 4; ++i) {
;           int kc = col0 + 8 * g + 4 * blk + i;
;           bool valid = (kc >= cs) && (kc <= cs + 15);
;           int bi = kc - c + 15;
;           bi = bi < 0 ? 0 : (bi > 30 ? 30 : bi);
;           float s = valid ? a[i] + bp[bi] : -1e30f;
;           a[i] = s;
;           mx = fmaxf(mx, s);
;         }
;         sl[kr][blk] = a;
;       }
;     }
	v_mfma_f32_16x16x32_f16 v[4:7], v[28:31], v[0:3], v[4:7]
	s_nop 7
	v_mov_b32_e32 v244, v4
	v_mov_b32_e32 v245, v5
	v_mov_b32_e32 v246, v6
	v_mov_b32_e32 v247, v7
	v_ashrrev_i32_e32 v9, 31, v8
	v_lshl_add_u64 v[28:29], v[8:9], 2, v[26:27]
	global_load_dword v248, v[28:29], off offset:928
	v_ashrrev_i32_e32 v13, 31, v12
	v_lshl_add_u64 v[28:29], v[12:13], 2, v[26:27]
	global_load_dword v249, v[28:29], off offset:928
	v_mov_b32_e32 v162, 0xf149f2ca
	v_mov_b32_e32 v163, 0xf149f2ca
	v_ashrrev_i32_e32 v15, 31, v14
	v_lshl_add_u64 v[4:5], v[14:15], 2, v[26:27]
	global_load_dword v250, v[4:5], off offset:928
	v_ashrrev_i32_e32 v17, 31, v16
	v_lshl_add_u64 v[4:5], v[16:17], 2, v[26:27]
	global_load_dword v251, v[4:5], off offset:928
	v_or_b32_e32 v4, 4, v19
	v_mad_i64_i32 v[28:29], s[24:25], v4, s22, v[90:91]
	global_load_dwordx4 v[4:7], v[28:29], off offset:768
	s_nop 0
	global_load_dwordx4 v[28:31], v[28:29], off offset:784
	v_mov_b32_e32 v166, 0xf149f2ca
	v_mov_b32_e32 v167, 0xf149f2ca
	s_waitcnt vmcnt(2)
	v_add_f32_e32 v248, v244, v248
	v_cndmask_b32_e64 v161, v161, v248, s[10:11]
	v_add_f32_e32 v249, v245, v249
	v_cndmask_b32_e64 v160, v160, v249, s[12:13]
	v_add_f32_e32 v250, v246, v250
	v_cndmask_b32_e64 v163, v163, v250, s[14:15]
	v_add_f32_e32 v251, v247, v251
	v_cndmask_b32_e64 v162, v162, v251, s[16:17]
	s_waitcnt vmcnt(1)
	v_mfma_f32_16x16x32_f16 v[4:7], v[4:7], v[64:67], 0
	s_waitcnt vmcnt(0)
	v_mfma_f32_16x16x32_f16 v[4:7], v[28:31], v[0:3], v[4:7]
	s_nop 7
	v_mov_b32_e32 v244, v4
	v_mov_b32_e32 v245, v5
	v_mov_b32_e32 v246, v6
	v_mov_b32_e32 v247, v7
	v_ashrrev_i32_e32 v19, 31, v18
	v_lshl_add_u64 v[28:29], v[18:19], 2, v[26:27]
	global_load_dword v248, v[28:29], off offset:928
	v_ashrrev_i32_e32 v21, 31, v20
	v_lshl_add_u64 v[28:29], v[20:21], 2, v[26:27]
	global_load_dword v249, v[28:29], off offset:928
	v_mov_b32_e32 v168, 0xf149f2ca
	v_mov_b32_e32 v169, 0xf149f2ca
	v_ashrrev_i32_e32 v23, 31, v22
	v_lshl_add_u64 v[4:5], v[22:23], 2, v[26:27]
	global_load_dword v250, v[4:5], off offset:928
	v_ashrrev_i32_e32 v25, 31, v24
	v_lshl_add_u64 v[4:5], v[24:25], 2, v[26:27]
	global_load_dword v251, v[4:5], off offset:928
	s_add_i32 s47, s41, 0xffffff80
	v_add_u32_e32 v19, s47, v11
	v_mul_hi_i32_i24_e32 v5, 0x1440, v19
	v_mul_i32_i24_e32 v4, 0x1440, v19
	v_lshl_add_u64 v[26:27], v[90:91], 0, v[4:5]
	global_load_dwordx4 v[4:7], v[26:27], off offset:768
	global_load_dwordx4 v[28:31], v[26:27], off offset:784
	v_add_u32_e32 v26, 0xffffff65, v10
	v_ashrrev_i32_e32 v27, 31, v26
	v_lshlrev_b64 v[26:27], 2, v[26:27]
	v_lshl_add_u64 v[26:27], v[92:93], 0, v[26:27]
	v_mov_b32_e32 v148, 0xf149f2ca
	v_mov_b32_e32 v149, 0xf149f2ca
	s_waitcnt vmcnt(2)
	v_add_f32_e32 v248, v244, v248
	v_cndmask_b32_e64 v167, v167, v248, s[18:19]
	v_add_f32_e32 v249, v245, v249
	v_cndmask_b32_e64 v166, v166, v249, s[20:21]
	v_add_f32_e32 v250, v246, v250
	v_cndmask_b32_e64 v169, v169, v250, s[34:35]
	v_add_f32_e32 v251, v247, v251
	v_cndmask_b32_e64 v168, v168, v251, s[6:7]
	s_waitcnt vmcnt(1)
	v_mfma_f32_16x16x32_f16 v[4:7], v[4:7], v[64:67], 0
	s_waitcnt vmcnt(0)
	v_mfma_f32_16x16x32_f16 v[4:7], v[28:31], v[0:3], v[4:7]
	s_nop 7
	v_mov_b32_e32 v244, v4
	v_mov_b32_e32 v245, v5
	v_mov_b32_e32 v246, v6
	v_mov_b32_e32 v247, v7
	v_ashrrev_i32_e32 v9, 31, v8
	v_lshl_add_u64 v[28:29], v[8:9], 2, v[26:27]
	global_load_dword v248, v[28:29], off offset:928
	v_ashrrev_i32_e32 v13, 31, v12
	v_lshl_add_u64 v[28:29], v[12:13], 2, v[26:27]
	global_load_dword v249, v[28:29], off offset:928
	v_mov_b32_e32 v151, 0xf149f2ca
	v_mov_b32_e32 v153, 0xf149f2ca
	v_ashrrev_i32_e32 v15, 31, v14
	v_lshl_add_u64 v[4:5], v[14:15], 2, v[26:27]
	global_load_dword v250, v[4:5], off offset:928
	v_ashrrev_i32_e32 v17, 31, v16
	v_lshl_add_u64 v[4:5], v[16:17], 2, v[26:27]
	global_load_dword v251, v[4:5], off offset:928
	v_or_b32_e32 v4, 4, v19
	v_mad_i64_i32 v[28:29], s[24:25], v4, s22, v[90:91]
	global_load_dwordx4 v[4:7], v[28:29], off offset:768
	s_nop 0
	global_load_dwordx4 v[28:31], v[28:29], off offset:784
	v_mov_b32_e32 v156, 0xf149f2ca
	v_mov_b32_e32 v157, 0xf149f2ca
	s_waitcnt vmcnt(2)
	v_add_f32_e32 v248, v244, v248
	v_cndmask_b32_e64 v149, v149, v248, s[10:11]
	v_add_f32_e32 v249, v245, v249
	v_cndmask_b32_e64 v148, v148, v249, s[12:13]
	v_add_f32_e32 v250, v246, v250
	v_cndmask_b32_e64 v153, v153, v250, s[14:15]
	v_add_f32_e32 v251, v247, v251
	v_cndmask_b32_e64 v151, v151, v251, s[16:17]
	s_waitcnt vmcnt(1)
	v_mfma_f32_16x16x32_f16 v[4:7], v[4:7], v[64:67], 0
	s_waitcnt vmcnt(0)
	v_mfma_f32_16x16x32_f16 v[4:7], v[28:31], v[0:3], v[4:7]
	s_nop 7
	v_mov_b32_e32 v244, v4
	v_mov_b32_e32 v245, v5
	v_mov_b32_e32 v246, v6
	v_mov_b32_e32 v247, v7
	v_ashrrev_i32_e32 v19, 31, v18
	v_lshl_add_u64 v[28:29], v[18:19], 2, v[26:27]
	global_load_dword v248, v[28:29], off offset:928
	v_ashrrev_i32_e32 v21, 31, v20
	v_lshl_add_u64 v[28:29], v[20:21], 2, v[26:27]
	global_load_dword v249, v[28:29], off offset:928
	v_mov_b32_e32 v158, 0xf149f2ca
	v_mov_b32_e32 v159, 0xf149f2ca
	v_ashrrev_i32_e32 v23, 31, v22
	v_lshl_add_u64 v[4:5], v[22:23], 2, v[26:27]
	global_load_dword v250, v[4:5], off offset:928
	v_ashrrev_i32_e32 v25, 31, v24
	v_lshl_add_u64 v[4:5], v[24:25], 2, v[26:27]
	global_load_dword v251, v[4:5], off offset:928
	s_sub_i32 s46, s41, 64
	v_add_u32_e32 v19, s46, v11
	v_mul_hi_i32_i24_e32 v5, 0x1440, v19
	v_mul_i32_i24_e32 v4, 0x1440, v19
	v_lshl_add_u64 v[26:27], v[90:91], 0, v[4:5]
	global_load_dwordx4 v[4:7], v[26:27], off offset:768
	global_load_dwordx4 v[28:31], v[26:27], off offset:784
	v_add_u32_e32 v26, 0xffffff84, v10
	v_ashrrev_i32_e32 v27, 31, v26
	v_lshlrev_b64 v[26:27], 2, v[26:27]
	v_lshl_add_u64 v[26:27], v[92:93], 0, v[26:27]
	v_mov_b32_e32 v80, 0xf149f2ca
	v_mov_b32_e32 v81, 0xf149f2ca
	s_waitcnt vmcnt(2)
; template <bool CL>
; __device__ __forceinline__ void natten_wave(const Params& p, int l, bool local, int b, int hh, int qrow0  ,
;                             int r, int ct, const f16* lK, const f16* lV) {
;     ...
; #pragma unroll
;     for (int kr = 0; kr < 8; ++kr) {
; #pragma unroll
;       for (int blk = 0; blk < 2; ++blk) {
;         int tk = (rs + kr) * GW + col0 + kperm + 4 * blk;
;         const f16* kp = proj + (size_t)(b * TL + tk) * PJ + RD + hh * HD + g * 16;
;         f16x8 k0 = *(const f16x8*)(kp);
;         f16x8 k1 = *(const f16x8*)(kp + 8);
;         f32x4 a = f32x4{0.f, 0.f, 0.f, 0.f};
;         a = __builtin_amdgcn_mfma_f32_16x16x32_f16(k0, qf[0], a, 0, 0, 0);
;         a = __builtin_amdgcn_mfma_f32_16x16x32_f16(k1, qf[1], a, 0, 0, 0);
;         const float* bp = rpb + (rs + kr - r + 7) * 31;
; #pragma unroll
;         for (int i = 0; i < 4; ++i) {
;           int kc = col0 + 8 * g + 4 * blk + i;
;           bool valid = (kc >= cs) && (kc <= cs + 15);
;           int bi = kc - c + 15;
;           bi = bi < 0 ? 0 : (bi > 30 ? 30 : bi);
;           float s = valid ? a[i] + bp[bi] : -1e30f;
;           a[i] = s;
;           mx = fmaxf(mx, s);
;         }
;         sl[kr][blk] = a;
;       }
;     }
	v_add_f32_e32 v248, v244, v248
	v_cndmask_b32_e64 v157, v157, v248, s[18:19]
	v_add_f32_e32 v249, v245, v249
	v_cndmask_b32_e64 v156, v156, v249, s[20:21]
	v_add_f32_e32 v250, v246, v250
	v_cndmask_b32_e64 v159, v159, v250, s[34:35]
	v_add_f32_e32 v251, v247, v251
	v_cndmask_b32_e64 v158, v158, v251, s[6:7]
	s_waitcnt vmcnt(1)
	v_mfma_f32_16x16x32_f16 v[4:7], v[4:7], v[64:67], 0
	s_waitcnt vmcnt(0)
	v_mfma_f32_16x16x32_f16 v[4:7], v[28:31], v[0:3], v[4:7]
	s_nop 7
	v_mov_b32_e32 v244, v4
	v_mov_b32_e32 v245, v5
	v_mov_b32_e32 v246, v6
	v_mov_b32_e32 v247, v7
	v_ashrrev_i32_e32 v9, 31, v8
	v_lshl_add_u64 v[28:29], v[8:9], 2, v[26:27]
	global_load_dword v248, v[28:29], off offset:928
	v_ashrrev_i32_e32 v13, 31, v12
	v_lshl_add_u64 v[28:29], v[12:13], 2, v[26:27]
	global_load_dword v249, v[28:29], off offset:928
	v_mov_b32_e32 v82, 0xf149f2ca
	v_mov_b32_e32 v83, 0xf149f2ca
	v_ashrrev_i32_e32 v15, 31, v14
	v_lshl_add_u64 v[4:5], v[14:15], 2, v[26:27]
	global_load_dword v250, v[4:5], off offset:928
	v_ashrrev_i32_e32 v17, 31, v16
	v_lshl_add_u64 v[4:5], v[16:17], 2, v[26:27]
	global_load_dword v251, v[4:5], off offset:928
	v_or_b32_e32 v4, 4, v19
	v_mad_i64_i32 v[28:29], s[24:25], v4, s22, v[90:91]
	global_load_dwordx4 v[4:7], v[28:29], off offset:768
	s_nop 0
	global_load_dwordx4 v[28:31], v[28:29], off offset:784
	v_mov_b32_e32 v150, 0xf149f2ca
	v_mov_b32_e32 v152, 0xf149f2ca
	s_waitcnt vmcnt(2)
	v_add_f32_e32 v248, v244, v248
	v_cndmask_b32_e64 v81, v81, v248, s[10:11]
	v_add_f32_e32 v249, v245, v249
	v_cndmask_b32_e64 v80, v80, v249, s[12:13]
	v_add_f32_e32 v250, v246, v250
	v_cndmask_b32_e64 v83, v83, v250, s[14:15]
	v_add_f32_e32 v251, v247, v251
	v_cndmask_b32_e64 v82, v82, v251, s[16:17]
	s_waitcnt vmcnt(1)
	v_mfma_f32_16x16x32_f16 v[4:7], v[4:7], v[64:67], 0
	s_waitcnt vmcnt(0)
	v_mfma_f32_16x16x32_f16 v[4:7], v[28:31], v[0:3], v[4:7]
	s_nop 7
	v_mov_b32_e32 v244, v4
	v_mov_b32_e32 v245, v5
	v_mov_b32_e32 v246, v6
	v_mov_b32_e32 v247, v7
	v_ashrrev_i32_e32 v19, 31, v18
	v_lshl_add_u64 v[28:29], v[18:19], 2, v[26:27]
	global_load_dword v248, v[28:29], off offset:928
	v_ashrrev_i32_e32 v21, 31, v20
	v_lshl_add_u64 v[28:29], v[20:21], 2, v[26:27]
	global_load_dword v249, v[28:29], off offset:928
	v_mov_b32_e32 v154, 0xf149f2ca
	v_mov_b32_e32 v155, 0xf149f2ca
	v_ashrrev_i32_e32 v23, 31, v22
	v_lshl_add_u64 v[4:5], v[22:23], 2, v[26:27]
	global_load_dword v250, v[4:5], off offset:928
	v_ashrrev_i32_e32 v25, 31, v24
	v_lshl_add_u64 v[4:5], v[24:25], 2, v[26:27]
	global_load_dword v251, v[4:5], off offset:928
	v_add_u32_e32 v19, s41, v11
	v_mul_hi_i32_i24_e32 v5, 0x1440, v19
	v_mul_i32_i24_e32 v4, 0x1440, v19
	v_lshl_add_u64 v[26:27], v[90:91], 0, v[4:5]
	global_load_dwordx4 v[4:7], v[26:27], off offset:768
	global_load_dwordx4 v[28:31], v[26:27], off offset:784
	v_add_u32_e32 v26, 0xffffffa3, v10
	v_ashrrev_i32_e32 v27, 31, v26
	v_lshlrev_b64 v[26:27], 2, v[26:27]
	v_lshl_add_u64 v[26:27], v[92:93], 0, v[26:27]
	v_mov_b32_e32 v140, 0xf149f2ca
	v_mov_b32_e32 v141, 0xf149f2ca
	s_waitcnt vmcnt(2)
	v_add_f32_e32 v248, v244, v248
	v_cndmask_b32_e64 v152, v152, v248, s[18:19]
	v_add_f32_e32 v249, v245, v249
	v_cndmask_b32_e64 v150, v150, v249, s[20:21]
	v_add_f32_e32 v250, v246, v250
	v_cndmask_b32_e64 v155, v155, v250, s[34:35]
	v_add_f32_e32 v251, v247, v251
	v_cndmask_b32_e64 v154, v154, v251, s[6:7]
	s_waitcnt vmcnt(1)
	v_mfma_f32_16x16x32_f16 v[4:7], v[4:7], v[64:67], 0
	s_waitcnt vmcnt(0)
	v_mfma_f32_16x16x32_f16 v[4:7], v[28:31], v[0:3], v[4:7]
	s_nop 7
	v_mov_b32_e32 v244, v4
	v_mov_b32_e32 v245, v5
	v_mov_b32_e32 v246, v6
	v_mov_b32_e32 v247, v7
	v_ashrrev_i32_e32 v9, 31, v8
	v_lshl_add_u64 v[28:29], v[8:9], 2, v[26:27]
	global_load_dword v248, v[28:29], off offset:928
	v_ashrrev_i32_e32 v13, 31, v12
	v_lshl_add_u64 v[28:29], v[12:13], 2, v[26:27]
	global_load_dword v249, v[28:29], off offset:928
	v_mov_b32_e32 v142, 0xf149f2ca
	v_mov_b32_e32 v143, 0xf149f2ca
	v_ashrrev_i32_e32 v15, 31, v14
	v_lshl_add_u64 v[4:5], v[14:15], 2, v[26:27]
	global_load_dword v250, v[4:5], off offset:928
	v_ashrrev_i32_e32 v17, 31, v16
	v_lshl_add_u64 v[4:5], v[16:17], 2, v[26:27]
	global_load_dword v251, v[4:5], off offset:928
	v_or_b32_e32 v4, 4, v19
	v_mad_i64_i32 v[28:29], s[24:25], v4, s22, v[90:91]
	global_load_dwordx4 v[4:7], v[28:29], off offset:768
	s_nop 0
	global_load_dwordx4 v[28:31], v[28:29], off offset:784
	v_mov_b32_e32 v144, 0xf149f2ca
	v_mov_b32_e32 v145, 0xf149f2ca
	s_waitcnt vmcnt(2)
	v_add_f32_e32 v248, v244, v248
	v_cndmask_b32_e64 v141, v141, v248, s[10:11]
	v_add_f32_e32 v249, v245, v249
	v_cndmask_b32_e64 v140, v140, v249, s[12:13]
	v_add_f32_e32 v250, v246, v250
	v_cndmask_b32_e64 v143, v143, v250, s[14:15]
	v_add_f32_e32 v251, v247, v251
	v_cndmask_b32_e64 v142, v142, v251, s[16:17]
	s_waitcnt vmcnt(1)
	v_mfma_f32_16x16x32_f16 v[4:7], v[4:7], v[64:67], 0
	s_waitcnt vmcnt(0)
	v_mfma_f32_16x16x32_f16 v[4:7], v[28:31], v[0:3], v[4:7]
	s_nop 7
	v_mov_b32_e32 v244, v4
	v_mov_b32_e32 v245, v5
	v_mov_b32_e32 v246, v6
	v_mov_b32_e32 v247, v7
	v_ashrrev_i32_e32 v19, 31, v18
	v_lshl_add_u64 v[28:29], v[18:19], 2, v[26:27]
	global_load_dword v248, v[28:29], off offset:928
	v_ashrrev_i32_e32 v21, 31, v20
	v_lshl_add_u64 v[28:29], v[20:21], 2, v[26:27]
	global_load_dword v249, v[28:29], off offset:928
	v_mov_b32_e32 v146, 0xf149f2ca
	v_mov_b32_e32 v147, 0xf149f2ca
	v_ashrrev_i32_e32 v23, 31, v22
	v_lshl_add_u64 v[4:5], v[22:23], 2, v[26:27]
	global_load_dword v250, v[4:5], off offset:928
	v_ashrrev_i32_e32 v25, 31, v24
	v_lshl_add_u64 v[4:5], v[24:25], 2, v[26:27]
	global_load_dword v251, v[4:5], off offset:928
	s_add_i32 s45, s41, 64
	v_add_u32_e32 v19, s45, v11
	v_mul_hi_i32_i24_e32 v5, 0x1440, v19
	v_mul_i32_i24_e32 v4, 0x1440, v19
	v_lshl_add_u64 v[26:27], v[90:91], 0, v[4:5]
	global_load_dwordx4 v[4:7], v[26:27], off offset:768
	global_load_dwordx4 v[28:31], v[26:27], off offset:784
	v_subrev_u32_e32 v26, 62, v10
	v_ashrrev_i32_e32 v27, 31, v26
	v_lshlrev_b64 v[26:27], 2, v[26:27]
	v_lshl_add_u64 v[26:27], v[92:93], 0, v[26:27]
	v_mov_b32_e32 v132, 0xf149f2ca
	v_mov_b32_e32 v133, 0xf149f2ca
	s_waitcnt vmcnt(2)
; template <bool CL>
; __device__ __forceinline__ void natten_wave(const Params& p, int l, bool local, int b, int hh, int qrow0  ,
;                             int r, int ct, const f16* lK, const f16* lV) {
;     ...
; #pragma unroll
;     for (int kr = 0; kr < 8; ++kr) {
; #pragma unroll
;       for (int blk = 0; blk < 2; ++blk) {
;         int tk = (rs + kr) * GW + col0 + kperm + 4 * blk;
;         const f16* kp = proj + (size_t)(b * TL + tk) * PJ + RD + hh * HD + g * 16;
;         f16x8 k0 = *(const f16x8*)(kp);
;         f16x8 k1 = *(const f16x8*)(kp + 8);
;         f32x4 a = f32x4{0.f, 0.f, 0.f, 0.f};
;         a = __builtin_amdgcn_mfma_f32_16x16x32_f16(k0, qf[0], a, 0, 0, 0);
;         a = __builtin_amdgcn_mfma_f32_16x16x32_f16(k1, qf[1], a, 0, 0, 0);
;         const float* bp = rpb + (rs + kr - r + 7) * 31;
; #pragma unroll
;         for (int i = 0; i < 4; ++i) {
;           int kc = col0 + 8 * g + 4 * blk + i;
;           bool valid = (kc >= cs) && (kc <= cs + 15);
;           int bi = kc - c + 15;
;           bi = bi < 0 ? 0 : (bi > 30 ? 30 : bi);
;           float s = valid ? a[i] + bp[bi] : -1e30f;
;           a[i] = s;
;           mx = fmaxf(mx, s);
;         }
;         sl[kr][blk] = a;
;       }
;     }
	v_add_f32_e32 v248, v244, v248
	v_cndmask_b32_e64 v145, v145, v248, s[18:19]
	v_add_f32_e32 v249, v245, v249
	v_cndmask_b32_e64 v144, v144, v249, s[20:21]
	v_add_f32_e32 v250, v246, v250
	v_cndmask_b32_e64 v147, v147, v250, s[34:35]
	v_add_f32_e32 v251, v247, v251
	v_cndmask_b32_e64 v146, v146, v251, s[6:7]
	s_waitcnt vmcnt(1)
	v_mfma_f32_16x16x32_f16 v[4:7], v[4:7], v[64:67], 0
	s_waitcnt vmcnt(0)
	v_mfma_f32_16x16x32_f16 v[4:7], v[28:31], v[0:3], v[4:7]
	s_nop 7
	v_mov_b32_e32 v244, v4
	v_mov_b32_e32 v245, v5
	v_mov_b32_e32 v246, v6
	v_mov_b32_e32 v247, v7
	v_ashrrev_i32_e32 v9, 31, v8
	v_lshl_add_u64 v[28:29], v[8:9], 2, v[26:27]
	global_load_dword v248, v[28:29], off offset:928
	v_ashrrev_i32_e32 v13, 31, v12
	v_lshl_add_u64 v[28:29], v[12:13], 2, v[26:27]
	global_load_dword v249, v[28:29], off offset:928
	v_mov_b32_e32 v134, 0xf149f2ca
	v_mov_b32_e32 v135, 0xf149f2ca
	v_ashrrev_i32_e32 v15, 31, v14
	v_lshl_add_u64 v[4:5], v[14:15], 2, v[26:27]
	global_load_dword v250, v[4:5], off offset:928
	v_ashrrev_i32_e32 v17, 31, v16
	v_lshl_add_u64 v[4:5], v[16:17], 2, v[26:27]
	global_load_dword v251, v[4:5], off offset:928
	v_or_b32_e32 v4, 4, v19
	v_mad_i64_i32 v[28:29], s[24:25], v4, s22, v[90:91]
	global_load_dwordx4 v[4:7], v[28:29], off offset:768
	s_nop 0
	global_load_dwordx4 v[28:31], v[28:29], off offset:784
	v_mov_b32_e32 v136, 0xf149f2ca
	v_mov_b32_e32 v137, 0xf149f2ca
	s_waitcnt vmcnt(2)
	v_add_f32_e32 v248, v244, v248
	v_cndmask_b32_e64 v133, v133, v248, s[10:11]
	v_add_f32_e32 v249, v245, v249
	v_cndmask_b32_e64 v132, v132, v249, s[12:13]
	v_add_f32_e32 v250, v246, v250
	v_cndmask_b32_e64 v135, v135, v250, s[14:15]
	v_add_f32_e32 v251, v247, v251
	v_cndmask_b32_e64 v134, v134, v251, s[16:17]
	s_waitcnt vmcnt(1)
	v_mfma_f32_16x16x32_f16 v[4:7], v[4:7], v[64:67], 0
	s_waitcnt vmcnt(0)
	v_mfma_f32_16x16x32_f16 v[4:7], v[28:31], v[0:3], v[4:7]
	s_nop 7
	v_mov_b32_e32 v244, v4
	v_mov_b32_e32 v245, v5
	v_mov_b32_e32 v246, v6
	v_mov_b32_e32 v247, v7
	v_ashrrev_i32_e32 v19, 31, v18
	v_lshl_add_u64 v[28:29], v[18:19], 2, v[26:27]
	global_load_dword v248, v[28:29], off offset:928
	v_ashrrev_i32_e32 v21, 31, v20
	v_lshl_add_u64 v[28:29], v[20:21], 2, v[26:27]
	global_load_dword v249, v[28:29], off offset:928
	v_mov_b32_e32 v138, 0xf149f2ca
	v_mov_b32_e32 v139, 0xf149f2ca
	v_ashrrev_i32_e32 v23, 31, v22
	v_lshl_add_u64 v[4:5], v[22:23], 2, v[26:27]
	global_load_dword v250, v[4:5], off offset:928
	v_ashrrev_i32_e32 v25, 31, v24
	v_lshl_add_u64 v[4:5], v[24:25], 2, v[26:27]
	global_load_dword v251, v[4:5], off offset:928
	s_add_i32 s44, s41, 0x80
	v_add_u32_e32 v19, s44, v11
	v_mul_hi_i32_i24_e32 v5, 0x1440, v19
	v_mul_i32_i24_e32 v4, 0x1440, v19
	v_lshl_add_u64 v[26:27], v[90:91], 0, v[4:5]
	global_load_dwordx4 v[4:7], v[26:27], off offset:768
	global_load_dwordx4 v[28:31], v[26:27], off offset:784
	v_subrev_u32_e32 v26, 31, v10
	v_ashrrev_i32_e32 v27, 31, v26
	v_lshlrev_b64 v[26:27], 2, v[26:27]
	v_lshl_add_u64 v[26:27], v[92:93], 0, v[26:27]
	v_mov_b32_e32 v84, 0xf149f2ca
	v_mov_b32_e32 v85, 0xf149f2ca
	s_waitcnt vmcnt(2)
	v_add_f32_e32 v248, v244, v248
	v_cndmask_b32_e64 v137, v137, v248, s[18:19]
	v_add_f32_e32 v249, v245, v249
	v_cndmask_b32_e64 v136, v136, v249, s[20:21]
	v_add_f32_e32 v250, v246, v250
	v_cndmask_b32_e64 v139, v139, v250, s[34:35]
	v_add_f32_e32 v251, v247, v251
	v_cndmask_b32_e64 v138, v138, v251, s[6:7]
	s_waitcnt vmcnt(1)
	v_mfma_f32_16x16x32_f16 v[4:7], v[4:7], v[64:67], 0
	s_waitcnt vmcnt(0)
	v_mfma_f32_16x16x32_f16 v[4:7], v[28:31], v[0:3], v[4:7]
	s_nop 7
	v_mov_b32_e32 v244, v4
	v_mov_b32_e32 v245, v5
	v_mov_b32_e32 v246, v6
	v_mov_b32_e32 v247, v7
	v_ashrrev_i32_e32 v9, 31, v8
	v_lshl_add_u64 v[28:29], v[8:9], 2, v[26:27]
	global_load_dword v248, v[28:29], off offset:928
	v_ashrrev_i32_e32 v13, 31, v12
	v_lshl_add_u64 v[28:29], v[12:13], 2, v[26:27]
	global_load_dword v249, v[28:29], off offset:928
	v_mov_b32_e32 v86, 0xf149f2ca
	v_mov_b32_e32 v87, 0xf149f2ca
	v_ashrrev_i32_e32 v15, 31, v14
	v_lshl_add_u64 v[4:5], v[14:15], 2, v[26:27]
	global_load_dword v250, v[4:5], off offset:928
	v_ashrrev_i32_e32 v17, 31, v16
	v_lshl_add_u64 v[4:5], v[16:17], 2, v[26:27]
	global_load_dword v251, v[4:5], off offset:928
	v_or_b32_e32 v4, 4, v19
	v_mad_i64_i32 v[28:29], s[24:25], v4, s22, v[90:91]
	global_load_dwordx4 v[4:7], v[28:29], off offset:768
	s_nop 0
	global_load_dwordx4 v[28:31], v[28:29], off offset:784
	v_mov_b32_e32 v128, 0xf149f2ca
	v_mov_b32_e32 v129, 0xf149f2ca
	s_waitcnt vmcnt(2)
; template <bool CL>
; __device__ __forceinline__ void natten_wave(const Params& p, int l, bool local, int b, int hh, int qrow0  ,
;                             int r, int ct, const f16* lK, const f16* lV) {
;     ...
; #pragma unroll
;     for (int kr = 0; kr < 8; ++kr) {
; #pragma unroll
;       for (int blk = 0; blk < 2; ++blk) {
;         int tk = (rs + kr) * GW + col0 + kperm + 4 * blk;
;         const f16* kp = proj + (size_t)(b * TL + tk) * PJ + RD + hh * HD + g * 16;
;         f16x8 k0 = *(const f16x8*)(kp);
;         f16x8 k1 = *(const f16x8*)(kp + 8);
;         f32x4 a = f32x4{0.f, 0.f, 0.f, 0.f};
;         a = __builtin_amdgcn_mfma_f32_16x16x32_f16(k0, qf[0], a, 0, 0, 0);
;         a = __builtin_amdgcn_mfma_f32_16x16x32_f16(k1, qf[1], a, 0, 0, 0);
;         const float* bp = rpb + (rs + kr - r + 7) * 31;
; #pragma unroll
;         for (int i = 0; i < 4; ++i) {
;           int kc = col0 + 8 * g + 4 * blk + i;
;           bool valid = (kc >= cs) && (kc <= cs + 15);
;           int bi = kc - c + 15;
;           bi = bi < 0 ? 0 : (bi > 30 ? 30 : bi);
;           float s = valid ? a[i] + bp[bi] : -1e30f;
;           a[i] = s;
;           mx = fmaxf(mx, s);
;         }
;         sl[kr][blk] = a;
;       }
;     }
	v_add_f32_e32 v248, v244, v248
	v_cndmask_b32_e64 v85, v85, v248, s[10:11]
	v_add_f32_e32 v249, v245, v249
	v_cndmask_b32_e64 v84, v84, v249, s[12:13]
	v_add_f32_e32 v250, v246, v250
	v_cndmask_b32_e64 v87, v87, v250, s[14:15]
	v_add_f32_e32 v251, v247, v251
	v_cndmask_b32_e64 v86, v86, v251, s[16:17]
	s_waitcnt vmcnt(1)
	v_mfma_f32_16x16x32_f16 v[4:7], v[4:7], v[64:67], 0
	s_waitcnt vmcnt(0)
	v_mfma_f32_16x16x32_f16 v[4:7], v[28:31], v[0:3], v[4:7]
	s_nop 7
	v_mov_b32_e32 v244, v4
	v_mov_b32_e32 v245, v5
	v_mov_b32_e32 v246, v6
	v_mov_b32_e32 v247, v7
	v_ashrrev_i32_e32 v19, 31, v18
	v_lshl_add_u64 v[28:29], v[18:19], 2, v[26:27]
	global_load_dword v248, v[28:29], off offset:928
	v_ashrrev_i32_e32 v21, 31, v20
	v_lshl_add_u64 v[28:29], v[20:21], 2, v[26:27]
	global_load_dword v249, v[28:29], off offset:928
	v_mov_b32_e32 v130, 0xf149f2ca
	v_mov_b32_e32 v131, 0xf149f2ca
	v_ashrrev_i32_e32 v23, 31, v22
	v_lshl_add_u64 v[4:5], v[22:23], 2, v[26:27]
	global_load_dword v250, v[4:5], off offset:928
	v_ashrrev_i32_e32 v25, 31, v24
	v_lshl_add_u64 v[4:5], v[24:25], 2, v[26:27]
	global_load_dword v251, v[4:5], off offset:928
	s_add_i32 s42, s41, 0xc0
	v_add_u32_e32 v19, s42, v11
	v_mul_hi_i32_i24_e32 v5, 0x1440, v19
	v_mul_i32_i24_e32 v4, 0x1440, v19
	v_lshl_add_u64 v[26:27], v[90:91], 0, v[4:5]
	global_load_dwordx4 v[4:7], v[26:27], off offset:768
	s_nop 0
	global_load_dwordx4 v[26:29], v[26:27], off offset:784
	v_ashrrev_i32_e32 v11, 31, v10
	v_lshlrev_b64 v[10:11], 2, v[10:11]
	v_lshl_add_u64 v[10:11], v[92:93], 0, v[10:11]
	v_mov_b32_e32 v120, 0xf149f2ca
	v_mov_b32_e32 v121, 0xf149f2ca
	s_waitcnt vmcnt(2)
	v_add_f32_e32 v248, v244, v248
	v_cndmask_b32_e64 v129, v129, v248, s[18:19]
	v_add_f32_e32 v249, v245, v249
	v_cndmask_b32_e64 v128, v128, v249, s[20:21]
	v_add_f32_e32 v250, v246, v250
	v_cndmask_b32_e64 v131, v131, v250, s[34:35]
	v_add_f32_e32 v251, v247, v251
	v_cndmask_b32_e64 v130, v130, v251, s[6:7]
	s_waitcnt vmcnt(1)
	v_mfma_f32_16x16x32_f16 v[4:7], v[4:7], v[64:67], 0
	s_waitcnt vmcnt(0)
	v_mfma_f32_16x16x32_f16 v[4:7], v[26:29], v[0:3], v[4:7]
	s_nop 7
	v_mov_b32_e32 v244, v4
	v_mov_b32_e32 v245, v5
	v_mov_b32_e32 v246, v6
	v_mov_b32_e32 v247, v7
	v_ashrrev_i32_e32 v9, 31, v8
	v_lshl_add_u64 v[8:9], v[8:9], 2, v[10:11]
	global_load_dword v248, v[8:9], off offset:928
	v_ashrrev_i32_e32 v13, 31, v12
	v_lshl_add_u64 v[8:9], v[12:13], 2, v[10:11]
	global_load_dword v249, v[8:9], off offset:928
	v_mov_b32_e32 v122, 0xf149f2ca
	v_mov_b32_e32 v123, 0xf149f2ca
	v_ashrrev_i32_e32 v15, 31, v14
	v_lshl_add_u64 v[4:5], v[14:15], 2, v[10:11]
	global_load_dword v250, v[4:5], off offset:928
	v_ashrrev_i32_e32 v17, 31, v16
	v_lshl_add_u64 v[4:5], v[16:17], 2, v[10:11]
	global_load_dword v251, v[4:5], off offset:928
	v_or_b32_e32 v4, 4, v19
	v_mad_i64_i32 v[8:9], s[100:101], v4, s22, v[90:91]
	global_load_dwordx4 v[4:7], v[8:9], off offset:768
	global_load_dwordx4 v[12:15], v[8:9], off offset:784
	v_mov_b32_e32 v124, 0xf149f2ca
	v_mov_b32_e32 v125, 0xf149f2ca
	s_waitcnt vmcnt(2)
	v_add_f32_e32 v248, v244, v248
	v_cndmask_b32_e64 v121, v121, v248, s[10:11]
	v_add_f32_e32 v249, v245, v249
	v_cndmask_b32_e64 v120, v120, v249, s[12:13]
	v_add_f32_e32 v250, v246, v250
	v_cndmask_b32_e64 v123, v123, v250, s[14:15]
	v_add_f32_e32 v251, v247, v251
	v_cndmask_b32_e64 v122, v122, v251, s[16:17]
	s_waitcnt vmcnt(1)
	v_mfma_f32_16x16x32_f16 v[4:7], v[4:7], v[64:67], 0
	s_waitcnt vmcnt(0)
	v_mfma_f32_16x16x32_f16 v[4:7], v[12:15], v[0:3], v[4:7]
	s_nop 7
	v_mov_b32_e32 v244, v4
	v_mov_b32_e32 v245, v5
	v_mov_b32_e32 v246, v6
	v_mov_b32_e32 v247, v7
	v_ashrrev_i32_e32 v19, 31, v18
	v_lshl_add_u64 v[8:9], v[18:19], 2, v[10:11]
	global_load_dword v248, v[8:9], off offset:928
	v_ashrrev_i32_e32 v21, 31, v20
	v_lshl_add_u64 v[8:9], v[20:21], 2, v[10:11]
	global_load_dword v249, v[8:9], off offset:928
	v_mov_b32_e32 v126, 0xf149f2ca
	v_mov_b32_e32 v127, 0xf149f2ca
	v_ashrrev_i32_e32 v23, 31, v22
	v_lshl_add_u64 v[4:5], v[22:23], 2, v[10:11]
	global_load_dword v250, v[4:5], off offset:928
	v_ashrrev_i32_e32 v25, 31, v24
	v_lshl_add_u64 v[4:5], v[24:25], 2, v[10:11]
	global_load_dword v251, v[4:5], off offset:928
	s_waitcnt vmcnt(0)
	v_add_f32_e32 v248, v244, v248
	v_cndmask_b32_e64 v125, v125, v248, s[18:19]
	v_add_f32_e32 v249, v245, v249
	v_cndmask_b32_e64 v124, v124, v249, s[20:21]
	v_add_f32_e32 v250, v246, v250
	v_cndmask_b32_e64 v127, v127, v250, s[34:35]
	v_add_f32_e32 v251, v247, v251
	v_cndmask_b32_e64 v126, v126, v251, s[6:7]
	s_branch .LBB0_548

; __device__ __forceinline__ void phase_prep(const Params& p, int l, float* smem) {
;     ...
;   {
;     const int g = lane >> 4, lq = lane & 15;
;     const int gw = blockIdx.x * 4 + __builtin_amdgcn_readfirstlane(tid >> 6), nw = gridDim.x * 4;
;     const f16* lwt = (const f16*)(p.ws + LWT_OFF) + (size_t)l * 4 * RD * 64;
;     for (int it = gw; it < (NTOK / 16) * 4; it += nw) {
;       const int m = it & 3, kind = m >> 1, z = m & 1;
;       const int row = (it >> 2) * 16 + lq;
;       int len, t;
;       if (row < NLAT) { len = TL; t = row % TL; } else { len = CTXL; t = (row - NLAT) % CTXL; }
;       const int cb = (kind == 0 ? 1152 : 1280) + 64 * z;
;       f16x8 xf[2];
.LBB0_713:
	s_or_b64 exec, exec, s[8:9]
	v_readfirstlane_b32 s6, v19
	s_ashr_i32 s8, s6, 6
	s_add_i32 s16, s8, s55
	s_cmpk_lg_u32 s26, 0x200
	s_cbranch_scc1 .Lrot_p2
	s_addk_i32 s16, 0x80
	s_and_b32 s16, s16, 0x7ff
.Lrot_p2:
	s_cmpk_gt_i32 s16, 0x207f
	s_cbranch_scc1 .LBB0_763
	v_readlane_b32 s10, v241, 0
	v_readlane_b32 s11, v241, 1
	s_load_dword s6, s[10:11], 0x10
	s_load_dword s9, s[10:11], 0x0
	v_bfe_u32 v2, v19, 4, 2
	v_lshlrev_b32_e32 v3, 4, v2
	v_and_b32_e32 v46, 15, v19
	s_waitcnt lgkmcnt(0)
	s_lshr_b32 s6, s6, 16
	s_cmp_lg_u32 s6, 0
	s_cselect_b64 s[6:7], -1, 0
	s_cmp_lg_u64 s[6:7], 0
	s_addc_u32 s9, s9, 0
	s_lshl_b32 s17, s9, 2
	s_and_b32 s12, s8, 1
	s_and_b32 s13, s8, 3
	s_cmp_lt_u32 s13, 2
	s_cselect_b64 s[6:7], -1, 0
	s_and_b64 s[10:11], s[6:7], exec
	s_movk_i32 s10, 0x500
	s_cselect_b32 s10, 0x480, s10
	s_lshl_b32 s11, s12, 6
	s_or_b32 s10, s10, s11
	v_or_b32_e32 v0, s10, v3
	v_lshlrev_b32_e32 v164, 2, v0
	s_mul_i32 s13, s13, 0xc000
	v_readlane_b32 s10, v241, 42
	v_lshl_add_u64 v[30:31], v[14:15], 0, v[164:165]
	v_lshl_add_u64 v[36:37], v[16:17], 0, v[164:165]
	v_lshlrev_b32_e32 v164, 1, v0
	v_readlane_b32 s11, v241, 43
	s_add_u32 s10, s10, s13
	v_lshl_add_u64 v[38:39], v[12:13], 0, v[164:165]
	s_addc_u32 s11, s11, 0
	v_lshlrev_b32_e32 v164, 7, v46
	v_lshl_add_u64 v[0:1], s[10:11], 0, v[164:165]
	v_lshlrev_b32_e32 v164, 5, v2
	s_mul_i32 s10, s12, 0x1860000
	v_lshl_add_u64 v[40:41], v[0:1], 0, v[164:165]
	v_lshl_or_b32 v164, v2, 3, s10
	s_lshl_b32 s8, s8, 2
	v_readlane_b32 s10, v241, 37
	s_add_i32 s18, s10, s8
	s_lshl_b32 s18, s16, 2
	s_lshl_b32 s19, s9, 4
	v_readlane_b32 s8, v241, 38
	v_readlane_b32 s9, v241, 39
	s_add_u32 s8, s8, s12
	s_addc_u32 s9, s9, 0
	s_mulk_i32 s9, 0x600
	s_mul_hi_u32 s10, s8, 0x600
	s_add_i32 s10, s10, s9
	s_mulk_i32 s8, 0x600
	v_or_b32_e32 v42, s8, v3
	v_mov_b32_e32 v43, s10

; __device__ __forceinline__ void phase_pool(const Params& p, int l, float* smem) {
;   const int lane = TIDX(p) & 63, gq = lane >> 4, lq = lane & 15;
;   const int gw = blockIdx.x * 4 + __builtin_amdgcn_readfirstlane(TIDX(p) >> 6), nw = gridDim.x * 4;
;   const f16* proj = (const f16*)(p.ws + PROJ_OFF);
;   const f16* pwt = (const f16*)(p.ws + PWT_OFF) + (size_t)l * 4 * 4096;
;   f16* br = (f16*)(p.ws + R2_OFF);
;   for (int it = gw; it < (NTOK / 16) * 4; it += nw) {
;     const int g = it & 3, w = 2 << g;
;     const int row = (it >> 2) * 16 + lq;
;     int len, t;
;     if (row < NLAT) { len = TL; t = row % TL; } else { len = CTXL; t = (row - NLAT) % CTXL; }
;     const f16* base = proj + (size_t)(row - t) * PJ + 2336 + g * 64 + gq * 16;
;     int lo = t - w / 2; lo = lo < 0 ? 0 : lo;
;     int hi = t + w / 2 - 1; hi = hi > len - 1 ? len - 1 : hi;
.LBB0_763:
	s_mov_b64 s[6:7], s[0:1]
	global_load_dword v0, v165, s[6:7] offset:272
	s_waitcnt vmcnt(0)
	s_nop 0
	v_add_u32_e32 v0, v0, v171
	s_nop 0
	v_readfirstlane_b32 s9, v0
	s_ashr_i32 s8, s9, 6
	s_add_i32 s8, s8, s55
	s_cmpk_lg_u32 s26, 0x200
	s_cbranch_scc1 .Lrot_pool
	s_addk_i32 s8, 0x100
	s_and_b32 s8, s8, 0x7ff
.Lrot_pool:
	s_cmpk_gt_i32 s8, 0x207f
	s_cbranch_scc1 .LBB0_774
	global_load_dwordx2 v[2:3], v165, s[6:7] offset:176
	global_load_dwordx2 v[8:9], v165, s[6:7] offset:264
	s_lshl_b64 s[6:7], s[4:5], 15
	v_bfe_u32 v1, v0, 4, 2
	v_lshlrev_b32_e32 v164, 5, v1
	v_and_b32_e32 v42, 15, v0
	s_lshl_b64 s[12:13], s[4:5], 10
	v_lshlrev_b32_e32 v0, 4, v1
	s_waitcnt vmcnt(1)
	v_lshl_add_u64 v[2:3], v[2:3], 0, s[12:13]
	s_waitcnt vmcnt(0)
	v_lshl_add_u64 v[4:5], v[8:9], 0, s[6:7]
	s_bfe_u32 s6, s9, 0x20006
	v_lshl_add_u64 v[4:5], v[4:5], 0, v[164:165]
	s_lshl_b32 s42, s6, 13
	v_lshl_add_u64 v[4:5], v[4:5], 0, s[42:43]
	v_lshlrev_b32_e32 v164, 7, v42
	s_lshl_b32 s9, 2, s6
	s_lshl_b32 s11, s6, 6
	s_lshl_b32 s10, 1, s6
	v_lshl_add_u64 v[4:5], v[4:5], 0, v[164:165]
	s_mov_b64 s[6:7], 0x1eee0000
	v_lshl_add_u64 v[10:11], v[4:5], 0, s[6:7]
	s_mov_b64 s[6:7], 0x1eee1000
	v_lshl_add_u64 v[12:13], v[4:5], 0, s[6:7]
	s_mov_b64 s[6:7], 0x1eee1010
	v_lshl_add_u64 v[14:15], v[4:5], 0, s[6:7]
	s_mov_b64 s[6:7], 0x1eee1800
	v_lshl_or_b32 v6, v1, 2, s11
	v_lshl_add_u64 v[16:17], v[4:5], 0, s[6:7]
	s_mov_b64 s[6:7], 0x1eee1810
	v_or_b32_e32 v24, 16, v6
	v_or_b32_e32 v26, 32, v6
	v_lshl_add_u64 v[18:19], v[4:5], 0, s[6:7]
	v_or_b32_e32 v4, 48, v6
	v_lshlrev_b32_e32 v164, 2, v6
	v_lshl_add_u64 v[20:21], v[2:3], 0, v[164:165]
	s_lshl_b32 s42, s11, 1
	v_lshlrev_b32_e32 v164, 1, v0
	v_lshlrev_b32_e32 v22, 1, v6
	v_lshlrev_b32_e32 v24, 1, v24
	v_lshlrev_b32_e32 v26, 1, v26
	v_lshlrev_b32_e32 v28, 1, v4
	s_branch .LBB0_766

; __global__ void __launch_bounds__(256, 2) mega(Params p_unused) {
	.amdhsa_kernel _Z4mega6Params
		.amdhsa_group_segment_fixed_size 73744
		.amdhsa_private_segment_fixed_size 0
		.amdhsa_kernarg_size 536
		.amdhsa_user_sgpr_count 2
		.amdhsa_user_sgpr_dispatch_ptr 0
		.amdhsa_user_sgpr_queue_ptr 0
		.amdhsa_user_sgpr_kernarg_segment_ptr 1
		.amdhsa_user_sgpr_dispatch_id 0
		.amdhsa_user_sgpr_kernarg_preload_length 0
		.amdhsa_user_sgpr_kernarg_preload_offset 0
		.amdhsa_user_sgpr_private_segment_size 0
		.amdhsa_uses_dynamic_stack 0
		.amdhsa_enable_private_segment 0
		.amdhsa_system_sgpr_workgroup_id_x 1
		.amdhsa_system_sgpr_workgroup_id_y 0
		.amdhsa_system_sgpr_workgroup_id_z 0
		.amdhsa_system_sgpr_workgroup_info 0
		.amdhsa_system_vgpr_workitem_id 2
		.amdhsa_next_free_vgpr 256
		.amdhsa_next_free_sgpr 102
		.amdhsa_accum_offset 256
		.amdhsa_reserve_vcc 1
		.amdhsa_float_round_mode_32 0
		.amdhsa_float_round_mode_16_64 0
		.amdhsa_float_denorm_mode_32 3
		.amdhsa_float_denorm_mode_16_64 3
		.amdhsa_dx10_clamp 1
		.amdhsa_ieee_mode 1
		.amdhsa_fp16_overflow 0
		.amdhsa_tg_split 0
		.amdhsa_exception_fp_ieee_invalid_op 0
		.amdhsa_exception_fp_denorm_src 0
		.amdhsa_exception_fp_ieee_div_zero 0
		.amdhsa_exception_fp_ieee_overflow 0
		.amdhsa_exception_fp_ieee_underflow 0
		.amdhsa_exception_fp_ieee_inexact 0
		.amdhsa_exception_int_div_zero 0
	.end_amdhsa_kernel

; __global__ void __launch_bounds__(256, 2) mega(Params p_unused) {
amdhsa.kernels:
  - .agpr_count:     0
    .args:
      - .offset:         0
        .size:           280
        .value_kind:     by_value
      - .offset:         280
        .size:           4
        .value_kind:     hidden_block_count_x
      - .offset:         284
        .size:           4
        .value_kind:     hidden_block_count_y
      - .offset:         288
        .size:           4
        .value_kind:     hidden_block_count_z
      - .offset:         292
        .size:           2
        .value_kind:     hidden_group_size_x
      - .offset:         294
        .size:           2
        .value_kind:     hidden_group_size_y
      - .offset:         296
        .size:           2
        .value_kind:     hidden_group_size_z
      - .offset:         298
        .size:           2
        .value_kind:     hidden_remainder_x
      - .offset:         300
        .size:           2
        .value_kind:     hidden_remainder_y
      - .offset:         302
        .size:           2
        .value_kind:     hidden_remainder_z
      - .offset:         320
        .size:           8
        .value_kind:     hidden_global_offset_x
      - .offset:         328
        .size:           8
        .value_kind:     hidden_global_offset_y
      - .offset:         336
        .size:           8
        .value_kind:     hidden_global_offset_z
      - .offset:         344
        .size:           2
        .value_kind:     hidden_grid_dims
      - .offset:         368
        .size:           8
        .value_kind:     hidden_multigrid_sync_arg
    .group_segment_fixed_size: 73744
    .kernarg_segment_align: 8
    .kernarg_segment_size: 536
    .language:       OpenCL C
    .language_version:
      - 2
      - 0
    .max_flat_workgroup_size: 256
    .name:           _Z4mega6Params
    .private_segment_fixed_size: 0
    .sgpr_count:     108
    .sgpr_spill_count: 56
    .symbol:         _Z4mega6Params.kd
    .uniform_work_group_size: 1
    .uses_dynamic_stack: false
    .vgpr_count:     256
    .vgpr_spill_count: 0
    .wavefront_size: 64
